# K1 phase: second resident block of a CU (bid bit 8) runs its ml_k1 units first and gdn_k1 units second, so co-resident blocks run different kernels side by side
# speedup vs baseline: 1.0334x; 1.0002x over previous
.LBB0_415:
	s_andn2_b64 vcc, exec, s[0:1]
	s_cbranch_vccnz .LBB0_474
	s_cmpk_lt_i32 s52, 0x60
	s_mov_b64 s[0:1], -1
	s_cbranch_scc1 .LBB0_462
	s_cmpk_gt_u32 s52, 0x45f
	s_cbranch_scc1 .LBB0_461
	v_readlane_b32 s0, v239, 53
	s_lshl_b32 s51, s0, 7
	s_sub_u32 s50, s52, 0x100
	s_cmp_lt_u32 s50, 0x60
	s_cbranch_scc0 .Lsi_work
	s_branch .LBB0_461
.Lsi_work:
	s_cmp_lt_u32 s52, 0x100
	s_cselect_b32 s50, 0, 0x60
	s_sub_u32 s57, s52, s50
	s_movk_i32 s50, 0x140
	s_add_i32 s54, s57, 0xfffffda0
	s_add_i32 s55, s57, 0xffffffa0
	s_mov_b32 s56, s57
	s_branch .LBB0_421

.LBB0_475:
	s_andn2_b64 vcc, exec, s[0:1]
	s_cbranch_vccnz .LBB0_572
	s_and_b32 s40, s91, 0x100
	s_lshl_b32 s40, s40, 2
	s_add_u32 s40, s40, s91
	s_branch .LBB0_479

.LBB0_478:
	s_mov_b32 s0, s96
	s_add_i32 s40, s0, s40
	s_and_b32 s40, s40, 0x7ff
	s_and_b32 s0, s91, 0x100
	s_lshl_b32 s0, s0, 2
	s_add_u32 s0, s0, s91
	s_cmp_eq_u32 s40, s0
	s_cbranch_scc1 .LBB0_572
